# phase-1 and final rmsnorm: wave sum via DPP/permlane adds instead of six serial ds_bpermute steps (on top of v47)
# baseline (speedup 1.0000x reference)
.LBB0_286:
	v_ashrrev_i32_e32 v17, 31, v16
	v_lshlrev_b64 v[28:29], 12, v[16:17]
	v_lshl_add_u64 v[40:41], v[18:19], 0, v[28:29]
	v_lshlrev_b64 v[28:29], 11, v[16:17]
	v_lshl_add_u64 v[44:45], v[20:21], 0, v[28:29]
	global_load_dwordx4 v[28:31], v[40:41], off
	global_load_dwordx4 v[32:35], v[40:41], off offset:1024
	global_load_dwordx4 v[56:59], v[40:41], off offset:2048
	global_load_dwordx4 v[60:63], v[40:41], off offset:3072
	v_add_u32_e32 v16, s6, v16
	s_waitcnt vmcnt(3)
	v_mov_b32_e32 v46, v29
	s_waitcnt vmcnt(2)
	v_mov_b32_e32 v47, v33
	v_mov_b32_e32 v42, v28
	v_mov_b32_e32 v43, v32
	v_pk_mul_f32 v[46:47], v[46:47], v[46:47]
	v_mov_b32_e32 v36, v30
	v_mov_b32_e32 v37, v34
	v_pk_fma_f32 v[42:43], v[42:43], v[42:43], v[46:47]
	v_mov_b32_e32 v38, v31
	v_mov_b32_e32 v39, v35
	v_pk_fma_f32 v[36:37], v[36:37], v[36:37], v[42:43]
	s_nop 0
	v_pk_fma_f32 v[46:47], v[38:39], v[38:39], v[36:37]
	v_add_f32_e32 v17, v46, v47
	s_waitcnt vmcnt(1)
	v_mov_b32_e32 v54, v57
	s_waitcnt vmcnt(0)
	v_mov_b32_e32 v55, v61
	v_mov_b32_e32 v52, v56
	v_mov_b32_e32 v53, v60
	v_pk_mul_f32 v[54:55], v[54:55], v[54:55]
	v_mov_b32_e32 v48, v58
	v_mov_b32_e32 v49, v62
	v_pk_fma_f32 v[52:53], v[52:53], v[52:53], v[54:55]
	v_mov_b32_e32 v50, v59
	v_mov_b32_e32 v51, v63
	v_pk_fma_f32 v[48:49], v[48:49], v[48:49], v[52:53]
	s_nop 0
	v_pk_fma_f32 v[48:49], v[50:51], v[50:51], v[48:49]
	s_nop 0
	v_add_f32_e32 v17, v17, v48
	v_add_f32_e32 v17, v17, v49
	s_nop 1
	v_add_f32_dpp v17, v17, v17 quad_perm:[1,0,3,2] row_mask:0xf bank_mask:0xf
	s_nop 1
	v_add_f32_dpp v17, v17, v17 quad_perm:[2,3,0,1] row_mask:0xf bank_mask:0xf
	s_nop 1
	v_add_f32_dpp v17, v17, v17 row_half_mirror row_mask:0xf bank_mask:0xf
	s_nop 1
	v_add_f32_dpp v17, v17, v17 row_mirror row_mask:0xf bank_mask:0xf
	v_mov_b32_e32 v46, v17
	s_nop 1
	v_permlane16_swap_b32_e32 v17, v46
	s_nop 1
	v_add_f32_e32 v17, v17, v46
	v_mov_b32_e32 v46, v17
	s_nop 1
	v_permlane32_swap_b32_e32 v17, v46
	s_nop 1
	v_add_f32_e32 v17, v17, v46
	v_fmamk_f32 v17, v17, 0x3a800000, v187
	v_cmp_gt_f32_e32 vcc, s79, v17
	v_mul_f32_e32 v46, 0x4b800000, v17
	s_nop 0
	v_cndmask_b32_e32 v17, v17, v46, vcc
	v_rsq_f32_e32 v17, v17
	s_nop 0
	v_mul_f32_e32 v46, 0x45800000, v17
	v_cndmask_b32_e32 v46, v17, v46, vcc
	v_pk_mul_f32 v[28:29], v[28:29], v[46:47] op_sel_hi:[1,0]
	v_pk_mul_f32 v[30:31], v[30:31], v[46:47] op_sel_hi:[1,0]
	v_pk_mul_f32 v[28:29], v[0:1], v[28:29]
	v_pk_mul_f32 v[30:31], v[2:3], v[30:31]
	v_cvt_pk_bf16_f32 v28, v28, v29
	v_cvt_pk_bf16_f32 v29, v30, v31
	global_store_dwordx2 v[44:45], v[28:29], off
	v_pk_mul_f32 v[28:29], v[32:33], v[46:47] op_sel_hi:[1,0]
	v_pk_mul_f32 v[30:31], v[34:35], v[46:47] op_sel_hi:[1,0]
	v_pk_mul_f32 v[28:29], v[4:5], v[28:29]
	v_pk_mul_f32 v[30:31], v[6:7], v[30:31]
	v_cvt_pk_bf16_f32 v28, v28, v29
	v_cvt_pk_bf16_f32 v29, v30, v31
	global_store_dwordx2 v[44:45], v[28:29], off offset:512
	v_pk_mul_f32 v[28:29], v[56:57], v[46:47] op_sel_hi:[1,0]
	v_pk_mul_f32 v[30:31], v[58:59], v[46:47] op_sel_hi:[1,0]
	v_pk_mul_f32 v[28:29], v[8:9], v[28:29]
	v_pk_mul_f32 v[30:31], v[10:11], v[30:31]
	v_cvt_pk_bf16_f32 v28, v28, v29
	v_cvt_pk_bf16_f32 v29, v30, v31
	global_store_dwordx2 v[44:45], v[28:29], off offset:1024
	v_pk_mul_f32 v[28:29], v[60:61], v[46:47] op_sel_hi:[1,0]
	v_pk_mul_f32 v[30:31], v[62:63], v[46:47] op_sel_hi:[1,0]
	v_pk_mul_f32 v[28:29], v[12:13], v[28:29]
	v_pk_mul_f32 v[30:31], v[14:15], v[30:31]
	v_cmp_lt_i32_e32 vcc, s25, v16
	v_cvt_pk_bf16_f32 v28, v28, v29
	v_cvt_pk_bf16_f32 v29, v30, v31
	s_or_b64 s[0:1], vcc, s[0:1]
	global_store_dwordx2 v[44:45], v[28:29], off offset:1536
	s_andn2_b64 exec, exec, s[0:1]
	s_cbranch_execnz .LBB0_286

.LBB0_2514:
	global_load_dwordx4 v[12:15], v[4:5], off
	global_load_dwordx4 v[16:19], v[4:5], off offset:1024
	global_load_dwordx4 v[20:23], v[4:5], off offset:2048
	global_load_dwordx4 v[24:27], v[4:5], off offset:3072
	global_load_dwordx4 v[28:31], v[2:3], off
	v_add_u32_e32 v0, s40, v0
	s_waitcnt vmcnt(4)
	v_mov_b32_e32 v34, v13
	s_waitcnt vmcnt(3)
	v_mov_b32_e32 v35, v17
	v_mov_b32_e32 v32, v12
	v_mov_b32_e32 v33, v16
	s_waitcnt vmcnt(2)
	v_mov_b32_e32 v42, v21
	s_waitcnt vmcnt(1)
	v_mov_b32_e32 v43, v25
	v_pk_mul_f32 v[34:35], v[34:35], v[34:35]
	v_mov_b32_e32 v36, v14
	v_mov_b32_e32 v37, v18
	v_mov_b32_e32 v40, v20
	v_mov_b32_e32 v41, v24
	v_pk_mul_f32 v[42:43], v[42:43], v[42:43]
	v_pk_fma_f32 v[32:33], v[32:33], v[32:33], v[34:35]
	v_mov_b32_e32 v38, v15
	v_mov_b32_e32 v39, v19
	v_mov_b32_e32 v44, v22
	v_mov_b32_e32 v45, v26
	v_pk_fma_f32 v[34:35], v[40:41], v[40:41], v[42:43]
	v_pk_fma_f32 v[32:33], v[36:37], v[36:37], v[32:33]
	v_mov_b32_e32 v46, v23
	v_mov_b32_e32 v47, v27
	v_pk_fma_f32 v[34:35], v[44:45], v[44:45], v[34:35]
	v_pk_fma_f32 v[32:33], v[38:39], v[38:39], v[32:33]
	v_pk_fma_f32 v[34:35], v[46:47], v[46:47], v[34:35]
	v_add_f32_e32 v32, v32, v33
	v_add_f32_e32 v32, v32, v34
	v_add_f32_e32 v32, v32, v35
	s_nop 1
	v_add_f32_dpp v32, v32, v32 quad_perm:[1,0,3,2] row_mask:0xf bank_mask:0xf
	s_nop 1
	v_add_f32_dpp v32, v32, v32 quad_perm:[2,3,0,1] row_mask:0xf bank_mask:0xf
	s_nop 1
	v_add_f32_dpp v32, v32, v32 row_half_mirror row_mask:0xf bank_mask:0xf
	s_nop 1
	v_add_f32_dpp v32, v32, v32 row_mirror row_mask:0xf bank_mask:0xf
	v_mov_b32_e32 v33, v32
	s_nop 1
	v_permlane16_swap_b32_e32 v32, v33
	s_nop 1
	v_add_f32_e32 v32, v32, v33
	v_mov_b32_e32 v33, v32
	s_nop 1
	v_permlane32_swap_b32_e32 v32, v33
	s_nop 1
	v_add_f32_e32 v32, v32, v33
	v_fmamk_f32 v32, v32, 0x3a800000, v1
	v_mul_f32_e32 v33, 0x4b800000, v32
	v_cmp_gt_f32_e32 vcc, s4, v32
	s_nop 1
	v_cndmask_b32_e32 v32, v32, v33, vcc
	v_rsq_f32_e32 v32, v32
	s_nop 0
	v_mul_f32_e32 v33, 0x45800000, v32
	v_cndmask_b32_e32 v32, v32, v33, vcc
	v_pk_mul_f32 v[12:13], v[32:33], v[12:13] op_sel_hi:[0,1]
	v_pk_mul_f32 v[14:15], v[32:33], v[14:15] op_sel_hi:[0,1]
	s_waitcnt vmcnt(0)
	v_pk_mul_f32 v[12:13], v[28:29], v[12:13]
	v_pk_mul_f32 v[14:15], v[30:31], v[14:15]
	global_store_dwordx4 v[4:5], v[12:15], off
	global_load_dwordx4 v[12:15], v[2:3], off offset:1024
	v_pk_mul_f32 v[16:17], v[32:33], v[16:17] op_sel_hi:[0,1]
	v_pk_mul_f32 v[18:19], v[32:33], v[18:19] op_sel_hi:[0,1]
	v_cmp_lt_i32_e32 vcc, s5, v0
	s_or_b64 s[2:3], vcc, s[2:3]
	s_waitcnt vmcnt(0)
	v_pk_mul_f32 v[12:13], v[12:13], v[16:17]
	v_pk_mul_f32 v[14:15], v[14:15], v[18:19]
	global_store_dwordx4 v[4:5], v[12:15], off offset:1024
	global_load_dwordx4 v[12:15], v[2:3], off offset:2048
	v_pk_mul_f32 v[16:17], v[32:33], v[20:21] op_sel_hi:[0,1]
	v_pk_mul_f32 v[18:19], v[32:33], v[22:23] op_sel_hi:[0,1]
	s_waitcnt vmcnt(0)
	v_pk_mul_f32 v[12:13], v[12:13], v[16:17]
	v_pk_mul_f32 v[14:15], v[14:15], v[18:19]
	global_store_dwordx4 v[4:5], v[12:15], off offset:2048
	global_load_dwordx4 v[12:15], v[2:3], off offset:3072
	v_pk_mul_f32 v[16:17], v[32:33], v[24:25] op_sel_hi:[0,1]
	v_pk_mul_f32 v[18:19], v[32:33], v[26:27] op_sel_hi:[0,1]
	s_waitcnt vmcnt(0)
	v_pk_mul_f32 v[12:13], v[12:13], v[16:17]
	v_pk_mul_f32 v[14:15], v[14:15], v[18:19]
	global_store_dwordx4 v[4:5], v[12:15], off offset:3072
	v_lshl_add_u64 v[4:5], v[4:5], 0, s[0:1]
	s_andn2_b64 exec, exec, s[2:3]
	s_cbranch_execnz .LBB0_2514
